# batched barrier-setup counter loads, mixout exchange stat loads issued together, phase_combine row loads hoisted above the weight computation
# baseline (speedup 1.0000x reference)
;     __device__ __forceinline__ void exchange(const f32x4 (&v)[2][2][4][2], const Unit& u, int wr, int wc, int fr, int fq, LAS unsigned char* lds, unsigned* xs, unsigned* cnt) const {
;     ...
;         if (tid < 256) { const unsigned* q = xs + ((size_t)(u.pm * BM + tid)) * 4; float t = 0.f;
; #pragma unroll
;             for (int k = 0; k < 4; ++k) t += __uint_as_float(__hip_atomic_load(q + k, __ATOMIC_RELAXED, __HIP_MEMORY_SCOPE_AGENT));
;             S[tid] = rsqrtf(t * (1.0f / 1024.0f) + EPS); }
.LBB0_198:
	s_or_b64 exec, exec, s[44:45]
	s_lshl_b32 s8, s4, 8
	s_barrier
	s_and_saveexec_b64 s[44:45], s[38:39]
	s_cbranch_execz .LBB0_200
	v_add_u32_e32 v132, s8, v130
	v_ashrrev_i32_e32 v133, 31, v132
	v_lshl_add_u64 v[132:133], v[132:133], 4, s[42:43]
	global_load_dword v131, v[132:133], off sc1
	global_load_dword v134, v[132:133], off offset:4 sc1
	global_load_dword v135, v[132:133], off offset:8 sc1
	global_load_dword v136, v[132:133], off offset:12 sc1
	v_lshl_add_u32 v130, v130, 2, 0
	s_waitcnt vmcnt(3)
	v_add_f32_e32 v131, 0, v131
	s_waitcnt vmcnt(2)
	v_add_f32_e32 v131, v131, v134
	s_waitcnt vmcnt(1)
	v_add_f32_e32 v131, v131, v135
	s_waitcnt vmcnt(0)
	v_add_f32_e32 v131, v131, v136
	v_fmamk_f32 v131, v131, 0x3a800000, v1
	v_cmp_gt_f32_e32 vcc, s33, v131
	v_mul_f32_e32 v132, 0x4b800000, v131
	s_nop 0
	v_cndmask_b32_e32 v131, v131, v132, vcc
	v_rsq_f32_e32 v131, v131
	s_nop 0
	v_mul_f32_e32 v132, 0x45800000, v131
	v_cndmask_b32_e32 v131, v131, v132, vcc
	ds_write_b32 v130, v131 offset:4096

;     __device__ __forceinline__ void exchange(const f32x4 (&v)[2][2][4][2], const Unit& u, int wr, int wc, int fr, int fq, LAS unsigned char* lds, unsigned* xs, unsigned* cnt) const {
;     ...
;         if (tid < 256) { const unsigned* q = xs + ((size_t)(u.pm * BM + tid)) * 4; float t = 0.f;
; #pragma unroll
;             for (int k = 0; k < 4; ++k) t += __uint_as_float(__hip_atomic_load(q + k, __ATOMIC_RELAXED, __HIP_MEMORY_SCOPE_AGENT));
;             S[tid] = rsqrtf(t * (1.0f / 1024.0f) + EPS); }
.LBB0_230:
	s_or_b64 exec, exec, s[38:39]
	v_readlane_b32 s4, v255, 29
	v_readlane_b32 s5, v255, 30
	s_lshl_b64 s[38:39], s[4:5], 10
	s_barrier
	s_and_saveexec_b64 s[40:41], s[36:37]
	s_cbranch_execz .LBB0_232
	v_lshl_add_u64 v[18:19], v[18:19], 4, s[30:31]
	global_load_dword v21, v[18:19], off sc1
	global_load_dword v134, v[18:19], off offset:4 sc1
	global_load_dword v135, v[18:19], off offset:8 sc1
	global_load_dword v136, v[18:19], off offset:12 sc1
	s_waitcnt vmcnt(3)
	v_add_f32_e32 v21, 0, v21
	s_waitcnt vmcnt(2)
	v_add_f32_e32 v21, v21, v134
	s_waitcnt vmcnt(1)
	v_add_f32_e32 v21, v21, v135
	s_waitcnt vmcnt(0)
	v_add_f32_e32 v18, v21, v136
	v_fmamk_f32 v18, v18, 0x3a800000, v1
	v_cmp_gt_f32_e32 vcc, s33, v18
	v_mul_f32_e32 v19, 0x4b800000, v18
	s_nop 0
	v_cndmask_b32_e32 v18, v18, v19, vcc
	v_rsq_f32_e32 v18, v18
	s_nop 0
	v_mul_f32_e32 v19, 0x45800000, v18
	v_cndmask_b32_e32 v18, v18, v19, vcc
	v_lshl_add_u32 v19, v20, 2, 0
	ds_write_b32 v19, v18 offset:4096

; __device__ __forceinline__ int get_tid() { int t = threadIdx.x; asm volatile("" : "+v"(t)); return t; }
; __device__ __forceinline__ void unpack8(const u32x4 w, float (&f)[8]) { f[0] = bflo(w.x); f[1] = bfhi(w.x); f[2] = bflo(w.y); f[3] = bfhi(w.y); f[4] = bflo(w.z); f[5] = bfhi(w.z); f[6] = bflo(w.w); f[7] = bfhi(w.w); }
; __device__ __forceinline__ u32x4 pack8(const float (&f)[8]) { u32x4 w; w.x = cvt_pk_bf16(f[0], f[1]); w.y = cvt_pk_bf16(f[2], f[3]); w.z = cvt_pk_bf16(f[4], f[5]); w.w = cvt_pk_bf16(f[6], f[7]); return w; }
; __device__ void phase_combine(const Params& P) {
;     ...
;     for (int idx0 = blockIdx.x * NTHR + get_tid(); idx0 < TH * 64; idx0 += 2 * stride) {
;         float lw[2][3]; u32x4 va[2], vb[2], vc[2]; bf16_t* pp[2]; bool ok[2];
; #pragma unroll
;         for (int k = 0; k < 2; ++k) { const int idx = idx0 + k * stride; ok[k] = idx < TH * 64; const int id2 = ok[k] ? idx : idx0;
;             const int tok = id2 >> 6, c8 = id2 & 63, hh = c8 >> 4, d0 = (c8 & 15) * 8;
;             lw[k][0] = LSE[tok * 12 + hh]; lw[k][1] = LSE[tok * 12 + 4 + hh]; lw[k][2] = LSE[tok * 12 + 8 + hh];
;             pp[k] = Z + (size_t)tok * ZC + ZDQ + hh * 128 + d0;
;             va[k] = *(const u32x4*)pp[k]; vb[k] = *(const u32x4*)(pp[k] + 512); vc[k] = *(const u32x4*)(pp[k] + 1024); }
; #pragma unroll
;         for (int k = 0; k < 2; ++k) {
;             const float mx = fmaxf(lw[k][0], fmaxf(lw[k][1], lw[k][2]));
;             float w0 = __expf(lw[k][0] - mx), w1 = __expf(lw[k][1] - mx), w2 = __expf(lw[k][2] - mx);
;             const float inv = 1.0f / (w0 + w1 + w2); w0 *= inv; w1 *= inv; w2 *= inv;
;             float a[8], b[8], c[8], o[8];
;             unpack8(va[k], a); unpack8(vb[k], b); unpack8(vc[k], c);
; #pragma unroll
;             for (int j = 0; j < 8; ++j) o[j] = w0 * a[j] + w1 * b[j] + w2 * c[j];
;             if (ok[k]) *(u32x4*)pp[k] = pack8(o);
;         }
.LBB0_449:
	v_add_u32_e32 v34, s82, v14
	s_mov_b32 s2, 0x100000
	v_cmp_gt_i32_e64 s[38:39], s2, v34
	v_readlane_b32 s6, v251, 33
	v_readlane_b32 s7, v251, 34
	v_cndmask_b32_e64 v6, v14, v34, s[38:39]
	v_ashrrev_i32_e32 v7, 6, v6
	v_bfe_u32 v8, v6, 4, 2
	v_mul_lo_u32 v2, v7, 12
	v_or_b32_e32 v2, v2, v8
	v_ashrrev_i32_e32 v3, 31, v2
	v_lshl_add_u64 v[4:5], v[2:3], 2, s[6:7]
	global_load_dword v36, v[4:5], off
	v_add_u32_e32 v4, 4, v2
	v_add_u32_e32 v2, 8, v2
	v_ashrrev_i32_e32 v5, 31, v4
	v_ashrrev_i32_e32 v3, 31, v2
	v_lshl_add_u64 v[4:5], v[4:5], 2, s[6:7]
	v_lshl_add_u64 v[2:3], v[2:3], 2, s[6:7]
	v_mov_b64_e32 v[16:17], s[74:75]
	global_load_dword v35, v[4:5], off
	global_load_dword v37, v[2:3], off
	v_mad_i64_i32 v[2:3], s[4:5], v7, s25, v[16:17]
	v_lshlrev_b32_e32 v194, 8, v8
	v_lshlrev_b32_e32 v4, 4, v6
	v_ashrrev_i32_e32 v20, 6, v14
	v_lshl_add_u64 v[2:3], v[2:3], 0, v[194:195]
	v_and_b32_e32 v194, 0xf0, v4
	v_mul_lo_u32 v15, v20, 12
	v_bfe_u32 v21, v14, 4, 2
	v_lshl_add_u64 v[2:3], v[2:3], 0, v[194:195]
	s_mov_b64 s[8:9], 0x7c59800
	s_mov_b32 s2, 0x7c59000
	v_or_b32_e32 v14, v15, v21
	v_lshl_add_u64 v[26:27], v[2:3], 0, s[8:9]
	v_add_co_u32_e32 v2, vcc, s2, v2
	v_ashrrev_i32_e32 v15, 31, v14
	s_nop 0
	v_addc_co_u32_e32 v3, vcc, 0, v3, vcc
	v_lshl_add_u64 v[18:19], v[14:15], 2, s[6:7]
	global_load_dwordx4 v[2:5], v[2:3], off offset:2048
	s_nop 0
	global_load_dwordx4 v[10:13], v[26:27], off offset:1024
	global_load_dwordx4 v[6:9], v[26:27], off offset:2048
	global_load_dword v42, v[18:19], off
	v_add_u32_e32 v18, 4, v14
	v_add_u32_e32 v14, 8, v14
	v_ashrrev_i32_e32 v19, 31, v18
	v_ashrrev_i32_e32 v15, 31, v14
	v_lshl_add_u64 v[18:19], v[18:19], 2, s[6:7]
	v_lshl_add_u64 v[14:15], v[14:15], 2, s[6:7]
	global_load_dword v43, v[18:19], off
	v_lshlrev_b32_e32 v194, 8, v21
	global_load_dword v44, v[14:15], off
	v_mad_i64_i32 v[14:15], s[4:5], v20, s25, v[16:17]
	v_and_b32_e32 v16, 0x78, v33
	v_lshl_add_u64 v[14:15], v[14:15], 0, v[194:195]
	v_lshlrev_b32_e32 v194, 1, v16
	v_lshl_add_u64 v[14:15], v[14:15], 0, v[194:195]
	v_add_co_u32_e32 v28, vcc, s2, v14
	v_lshl_add_u64 v[22:23], v[14:15], 0, s[8:9]
	s_nop 0
	v_addc_co_u32_e32 v29, vcc, 0, v15, vcc
	global_load_dwordx4 v[14:17], v[28:29], off offset:2048
	global_load_dwordx4 v[18:21], v[22:23], off offset:1024
	global_load_dwordx4 v[22:25], v[22:23], off offset:2048
	s_waitcnt vmcnt(3)
	v_max3_f32 v45, v42, v43, v44
	v_sub_f32_e32 v44, v44, v45
	v_mul_f32_e32 v44, 0x3fb8aa3b, v44
	v_sub_f32_e32 v46, v42, v45
	v_exp_f32_e32 v30, v44
	v_sub_f32_e32 v44, v43, v45
	v_mul_f32_e32 v46, 0x3fb8aa3b, v46
	v_mul_f32_e32 v44, 0x3fb8aa3b, v44
	v_exp_f32_e32 v31, v46
	v_exp_f32_e32 v43, v44
	s_nop 0
	v_add_f32_e32 v44, v31, v43
	v_add_f32_e32 v44, v30, v44
	v_div_scale_f32 v45, s[4:5], v44, v44, 1.0
	v_rcp_f32_e32 v46, v45
	s_nop 0
	v_fma_f32 v42, -v45, v46, 1.0
	v_fmac_f32_e32 v46, v42, v46
	v_div_scale_f32 v42, vcc, 1.0, v44, 1.0
	v_mul_f32_e32 v47, v42, v46
	v_fma_f32 v48, -v45, v47, v42
	v_fmac_f32_e32 v47, v48, v46
	v_fma_f32 v45, -v45, v47, v42
	v_div_fmas_f32 v45, v45, v46, v47
	v_div_fixup_f32 v32, v45, v44, 1.0
	v_mul_f32_e32 v40, v43, v32
	v_pk_mul_f32 v[30:31], v[30:31], v[32:33] op_sel_hi:[1,0]
	s_waitcnt vmcnt(2)
	v_and_b32_e32 v39, 0xffff0000, v17
	s_waitcnt vmcnt(1)
	v_and_b32_e32 v41, 0xffff0000, v21
	v_lshlrev_b32_e32 v21, 16, v21
	s_waitcnt vmcnt(0)
	v_and_b32_e32 v38, 0xffff0000, v25
	v_pk_mul_f32 v[38:39], v[30:31], v[38:39]
	s_nop 0
	v_fma_f32 v32, v40, v41, v39
	v_add_f32_e32 v32, v38, v32
	v_lshlrev_b32_e32 v39, 16, v17
	v_lshlrev_b32_e32 v38, 16, v25
	v_pk_mul_f32 v[38:39], v[30:31], v[38:39]
	s_nop 0
	v_fma_f32 v17, v40, v21, v39
	v_add_f32_e32 v21, v38, v17
	v_and_b32_e32 v39, 0xffff0000, v16
	v_and_b32_e32 v38, 0xffff0000, v24
	v_and_b32_e32 v17, 0xffff0000, v20
	v_pk_mul_f32 v[38:39], v[30:31], v[38:39]
	v_lshlrev_b32_e32 v20, 16, v20
	v_fma_f32 v17, v40, v17, v39
	v_add_f32_e32 v25, v38, v17
	v_lshlrev_b32_e32 v17, 16, v16
	v_lshlrev_b32_e32 v16, 16, v24
	v_pk_mul_f32 v[16:17], v[30:31], v[16:17]
	v_and_b32_e32 v24, 0xffff0000, v19
	v_fma_f32 v17, v40, v20, v17
	v_add_f32_e32 v20, v16, v17
	v_and_b32_e32 v17, 0xffff0000, v15
	v_and_b32_e32 v16, 0xffff0000, v23
	v_pk_mul_f32 v[16:17], v[30:31], v[16:17]
	v_lshlrev_b32_e32 v19, 16, v19
	v_fma_f32 v17, v40, v24, v17
	v_add_f32_e32 v24, v16, v17
	v_lshlrev_b32_e32 v17, 16, v15
	v_lshlrev_b32_e32 v16, 16, v23
	v_pk_mul_f32 v[16:17], v[30:31], v[16:17]
	s_nop 0
	v_fma_f32 v15, v40, v19, v17
	v_add_f32_e32 v19, v16, v15
	v_and_b32_e32 v17, 0xffff0000, v14
	v_and_b32_e32 v16, 0xffff0000, v22
	v_and_b32_e32 v15, 0xffff0000, v18
	v_pk_mul_f32 v[16:17], v[30:31], v[16:17]
	s_nop 0
	v_fma_f32 v15, v40, v15, v17
	v_add_f32_e32 v16, v16, v15
	v_lshlrev_b32_e32 v15, 16, v14
	v_lshlrev_b32_e32 v14, 16, v22
	v_lshlrev_b32_e32 v17, 16, v18
	v_pk_mul_f32 v[14:15], v[30:31], v[14:15]
	s_nop 0
	v_fma_f32 v15, v40, v17, v15
	v_add_f32_e32 v14, v14, v15
	v_cvt_pk_bf16_f32 v14, v14, v16
	v_cvt_pk_bf16_f32 v15, v19, v24
	v_cvt_pk_bf16_f32 v16, v20, v25
	v_cvt_pk_bf16_f32 v17, v21, v32
	global_store_dwordx4 v[28:29], v[14:17], off offset:2048
	s_and_saveexec_b64 s[40:41], s[38:39]
	s_cbranch_execz .LBB0_448
; __device__ __forceinline__ void unpack8(const u32x4 w, float (&f)[8]) { f[0] = bflo(w.x); f[1] = bfhi(w.x); f[2] = bflo(w.y); f[3] = bfhi(w.y); f[4] = bflo(w.z); f[5] = bfhi(w.z); f[6] = bflo(w.w); f[7] = bfhi(w.w); }
; __device__ __forceinline__ u32x4 pack8(const float (&f)[8]) { u32x4 w; w.x = cvt_pk_bf16(f[0], f[1]); w.y = cvt_pk_bf16(f[2], f[3]); w.z = cvt_pk_bf16(f[4], f[5]); w.w = cvt_pk_bf16(f[6], f[7]); return w; }
; __device__ void phase_combine(const Params& P) {
;     ...
;         for (int k = 0; k < 2; ++k) {
;             const float mx = fmaxf(lw[k][0], fmaxf(lw[k][1], lw[k][2]));
;             float w0 = __expf(lw[k][0] - mx), w1 = __expf(lw[k][1] - mx), w2 = __expf(lw[k][2] - mx);
;             const float inv = 1.0f / (w0 + w1 + w2); w0 *= inv; w1 *= inv; w2 *= inv;
;             float a[8], b[8], c[8], o[8];
;             unpack8(va[k], a); unpack8(vb[k], b); unpack8(vc[k], c);
; #pragma unroll
;             for (int j = 0; j < 8; ++j) o[j] = w0 * a[j] + w1 * b[j] + w2 * c[j];
;             if (ok[k]) *(u32x4*)pp[k] = pack8(o);
;         }
	v_max3_f32 v14, v36, v35, v37
	v_sub_f32_e32 v15, v36, v14
	v_sub_f32_e32 v16, v37, v14
	v_sub_f32_e32 v14, v35, v14
	v_mul_f32_e32 v15, 0x3fb8aa3b, v15
	v_mul_f32_e32 v14, 0x3fb8aa3b, v14
	v_exp_f32_e32 v15, v15
	v_mul_f32_e32 v16, 0x3fb8aa3b, v16
	v_exp_f32_e32 v17, v14
	v_exp_f32_e32 v14, v16
	v_add_f32_e32 v16, v15, v17
	v_add_f32_e32 v16, v14, v16
	v_div_scale_f32 v18, s[4:5], v16, v16, 1.0
	v_rcp_f32_e32 v19, v18
	s_nop 0
	v_fma_f32 v20, -v18, v19, 1.0
	v_fmac_f32_e32 v19, v20, v19
	v_div_scale_f32 v20, vcc, 1.0, v16, 1.0
	v_mul_f32_e32 v21, v20, v19
	v_fma_f32 v22, -v18, v21, v20
	v_fmac_f32_e32 v21, v22, v19
	v_fma_f32 v18, -v18, v21, v20
	v_div_fmas_f32 v18, v18, v19, v21
	v_div_fixup_f32 v16, v18, v16, 1.0
	v_mul_f32_e32 v18, v17, v16
	v_pk_mul_f32 v[14:15], v[14:15], v[16:17] op_sel_hi:[1,0]
	v_and_b32_e32 v17, 0xffff0000, v5
	v_and_b32_e32 v16, 0xffff0000, v9
	v_and_b32_e32 v19, 0xffff0000, v13
	v_pk_mul_f32 v[16:17], v[14:15], v[16:17]
	v_lshlrev_b32_e32 v13, 16, v13
	v_fma_f32 v17, v18, v19, v17
	v_add_f32_e32 v19, v16, v17
	v_lshlrev_b32_e32 v17, 16, v5
	v_lshlrev_b32_e32 v16, 16, v9
	v_pk_mul_f32 v[16:17], v[14:15], v[16:17]
	s_nop 0
	v_fma_f32 v5, v18, v13, v17
	v_add_f32_e32 v9, v16, v5
	v_and_b32_e32 v17, 0xffff0000, v4
	v_and_b32_e32 v16, 0xffff0000, v8
	v_and_b32_e32 v5, 0xffff0000, v12
	v_pk_mul_f32 v[16:17], v[14:15], v[16:17]
	v_lshlrev_b32_e32 v12, 16, v12
	v_fma_f32 v5, v18, v5, v17
	v_add_f32_e32 v13, v16, v5
	v_lshlrev_b32_e32 v5, 16, v4
	v_lshlrev_b32_e32 v4, 16, v8
	v_pk_mul_f32 v[4:5], v[14:15], v[4:5]
	s_nop 0
	v_fma_f32 v5, v18, v12, v5
	v_add_f32_e32 v8, v4, v5
	v_and_b32_e32 v5, 0xffff0000, v3
	v_and_b32_e32 v4, 0xffff0000, v7
	v_and_b32_e32 v12, 0xffff0000, v11
	v_pk_mul_f32 v[4:5], v[14:15], v[4:5]
	v_lshlrev_b32_e32 v11, 16, v11
	v_fma_f32 v5, v18, v12, v5
	v_add_f32_e32 v12, v4, v5
	v_lshlrev_b32_e32 v5, 16, v3
	v_lshlrev_b32_e32 v4, 16, v7
	v_pk_mul_f32 v[4:5], v[14:15], v[4:5]
	s_nop 0
	v_fma_f32 v3, v18, v11, v5
	v_add_f32_e32 v7, v4, v3
	v_and_b32_e32 v5, 0xffff0000, v2
	v_and_b32_e32 v4, 0xffff0000, v6
	v_and_b32_e32 v3, 0xffff0000, v10
	v_pk_mul_f32 v[4:5], v[14:15], v[4:5]
	s_nop 0
	v_fma_f32 v3, v18, v3, v5
	v_add_f32_e32 v4, v4, v3
	v_lshlrev_b32_e32 v3, 16, v2
	v_lshlrev_b32_e32 v2, 16, v6
	v_lshlrev_b32_e32 v5, 16, v10
	v_pk_mul_f32 v[2:3], v[14:15], v[2:3]
	s_nop 0
	v_fma_f32 v3, v18, v5, v3
	v_add_f32_e32 v2, v2, v3
	v_cvt_pk_bf16_f32 v2, v2, v4
	v_cvt_pk_bf16_f32 v3, v7, v12
	v_cvt_pk_bf16_f32 v4, v8, v13
	v_cvt_pk_bf16_f32 v5, v9, v19
	global_store_dwordx4 v[26:27], v[2:5], off
	s_branch .LBB0_448

; __device__ __forceinline__ unsigned xb_ld(unsigned* p)              { return __hip_atomic_load(p, __ATOMIC_RELAXED, __HIP_MEMORY_SCOPE_AGENT); }
; __device__ __forceinline__ void xcd_barrier_complete(unsigned* bar, unsigned x, unsigned& nloc, unsigned& nx) {
;     const unsigned G = gridDim.x * gridDim.y * gridDim.z;
;     unsigned sum, cnt, mine, sp = 0u;
;     for (;;) {
;         sum = 0u; cnt = 0u; mine = 0u;
; #pragma unroll
;         for (unsigned j = 0; j < 16; ++j) { const unsigned c = xb_ld(&bar[XB_XCNT(j)]); sum += c; cnt += (c > 0u) ? 1u : 0u; mine = (j == x) ? c : mine; }
;         if (sum == G) break;
;         __builtin_amdgcn_s_sleep(1);
;         if ((++sp & 255u) == 0u) { if (xb_ld(&bar[XB_TMO])) break; if (sp > XB_SPIN_CAP) { atomicAdd(&bar[XB_TMO], 1u); break; } }
;     }
.LBB0_763:
	v_readlane_b32 s4, v252, 45
	v_readlane_b32 s5, v252, 46
	s_mov_b64 s[30:31], -1
	s_mov_b64 s[36:37], -1
	s_waitcnt lgkmcnt(0)
	s_nop 4
	global_load_dword v2, v195, s[4:5] sc1
	global_load_dword v3, v195, s[4:5] offset:256 sc1
	global_load_dword v4, v195, s[4:5] offset:512 sc1
	global_load_dword v5, v195, s[4:5] offset:768 sc1
	global_load_dword v6, v195, s[4:5] offset:1024 sc1
	global_load_dword v7, v195, s[4:5] offset:1280 sc1
	global_load_dword v8, v195, s[4:5] offset:1536 sc1
	global_load_dword v9, v195, s[4:5] offset:1792 sc1
	global_load_dword v10, v195, s[4:5] offset:2048 sc1
	global_load_dword v11, v195, s[4:5] offset:2304 sc1
	global_load_dword v12, v195, s[4:5] offset:2560 sc1
	global_load_dword v13, v195, s[4:5] offset:2816 sc1
	global_load_dword v14, v195, s[4:5] offset:3072 sc1
	global_load_dword v15, v195, s[4:5] offset:3328 sc1
	global_load_dword v16, v195, s[4:5] offset:3584 sc1
	global_load_dword v17, v195, s[4:5] offset:3840 sc1
	v_readlane_b32 s4, v254, 54
	s_waitcnt vmcnt(0)
	v_add_u32_e32 v18, v3, v2
	v_add_u32_e32 v18, v18, v4
	v_add_u32_e32 v18, v18, v5
	v_add_u32_e32 v18, v18, v6
	v_add_u32_e32 v18, v18, v7
	v_add_u32_e32 v18, v18, v8
	v_add_u32_e32 v18, v18, v9
	v_add_u32_e32 v18, v18, v10
	v_add_u32_e32 v18, v18, v11
	v_add_u32_e32 v18, v18, v12
	v_add_u32_e32 v18, v18, v13
	v_add_u32_e32 v18, v18, v14
	v_add_u32_e32 v18, v18, v15
	v_add_u32_e32 v18, v18, v16
	v_add_u32_e32 v18, v18, v17
	v_cmp_eq_u32_e32 vcc, s4, v18
	s_cbranch_vccnz .LBB0_762
	s_and_b32 s4, s2, 0xff
	s_cmp_eq_u32 s4, 0
	s_mov_b64 s[38:39], -1
	s_sleep 1
	s_cbranch_scc0 .LBB0_767
	v_readlane_b32 s4, v252, 43
	v_readlane_b32 s5, v252, 44
	s_nop 4
	global_load_dword v18, v195, s[4:5] sc1
	s_waitcnt vmcnt(0)
	v_cmp_eq_u32_e32 vcc, 0, v18
	s_cbranch_vccnz .LBB0_769
	s_mov_b64 s[38:39], 0
